# remaining serialized per-row rstd load chains (DKVQ wave_rstd, RowScale 8 loads, wave_rstd<8>) issued back to back
# speedup vs baseline: 1.0049x; 1.0049x over previous
.LBB0_579:
	v_mov_b32_e32 v152, v155
	s_lshl_b32 s0, s11, 8
	v_ashrrev_i32_e32 v128, 31, v152
	v_lshrrev_b32_e32 v128, 30, v128
	v_add_u32_e32 v128, v152, v128
	s_waitcnt vmcnt(0)
	v_ashrrev_i32_e32 v170, 2, v128
	s_add_i32 s0, s0, s66
	v_and_b32_e32 v128, 0x3ffffffc, v128
	v_lshlrev_b32_e32 v130, 1, v170
	v_sub_u32_e32 v128, v152, v128
	v_and_b32_e32 v130, 0xffffff80, v130
	v_and_or_b32 v131, v170, 63, s0
	v_lshlrev_b32_e32 v128, 2, v128
	v_add_u32_e32 v130, v131, v130
	v_ashrrev_i32_e32 v129, 31, v128
	v_ashrrev_i32_e32 v131, 31, v130
	v_lshl_add_u64 v[128:129], v[128:129], 2, s[20:21]
	v_lshlrev_b64 v[160:161], 6, v[130:131]
	v_lshl_add_u64 v[160:161], v[128:129], 0, v[160:161]
	global_load_dwordx4 v[220:223], v[160:161], off offset:1024
	global_load_dwordx4 v[224:227], v[160:161], off offset:2048
	global_load_dwordx4 v[228:231], v[160:161], off offset:3072
	v_add_co_u32_e32 v216, vcc, 0x2000, v160
	v_addc_co_u32_e32 v217, vcc, 0, v161, vcc
	global_load_dwordx4 v[232:235], v[216:217], off
	global_load_dwordx4 v[236:239], v[216:217], off offset:1024
	global_load_dwordx4 v[240:243], v[216:217], off offset:2048
	global_load_dwordx4 v[244:247], v[216:217], off offset:3072
	global_load_dwordx4 v[160:163], v[160:161], off
	v_and_b32_e32 v154, 64, v219
	v_add_u32_e32 v159, 64, v154
	v_add_u32_e32 v130, 0x80, v130
	s_add_i32 s75, s10, s58
	s_add_i32 s64, s75, -2
	s_cmp_eq_u32 s64, 0
	s_mov_b64 s[38:39], -1
	s_mov_b64 s[16:17], 0
	s_mov_b64 s[10:11], 0
	s_waitcnt vmcnt(0)
	v_add_f32_e32 v131, v160, v161
	v_add_f32_e32 v156, v162, v163
	v_add_f32_e32 v131, v131, v156
	v_xor_b32_e32 v156, 1, v219
	v_cmp_lt_i32_e32 vcc, v156, v159
	s_nop 1
	v_cndmask_b32_e32 v156, v219, v156, vcc
	v_lshlrev_b32_e32 v160, 2, v156
	ds_bpermute_b32 v156, v160, v131
	s_waitcnt lgkmcnt(0)
	v_add_f32_e32 v131, v131, v156
	v_xor_b32_e32 v156, 2, v219
	v_cmp_lt_i32_e32 vcc, v156, v159
	s_nop 1
	v_cndmask_b32_e32 v156, v219, v156, vcc
	v_lshlrev_b32_e32 v158, 2, v156
	ds_bpermute_b32 v156, v158, v131
	s_waitcnt lgkmcnt(0)
	v_add_f32_e32 v131, v131, v156
	v_fmamk_f32 v131, v131, 0x3a800000, v200
	v_rsq_f32_e32 v156, v131
	v_add_u32_e32 v131, 16, v170
	v_lshlrev_b32_e32 v161, 1, v131
	v_and_b32_e32 v161, 0xffffff80, v161
	v_and_or_b32 v131, v131, 63, s0
	v_add_u32_e32 v162, v131, v161
	v_ashrrev_i32_e32 v163, 31, v162
	v_lshlrev_b64 v[162:163], 6, v[162:163]
	v_lshl_add_u64 v[162:163], v[128:129], 0, v[162:163]
	s_waitcnt vmcnt(0)
	v_add_f32_e32 v131, v220, v221
	v_add_f32_e32 v161, v222, v223
	v_add_f32_e32 v131, v131, v161
	ds_bpermute_b32 v161, v160, v131
	s_waitcnt lgkmcnt(0)
	v_add_f32_e32 v131, v131, v161
	ds_bpermute_b32 v161, v158, v131
	s_waitcnt lgkmcnt(0)
	v_add_f32_e32 v131, v131, v161
	v_fmamk_f32 v131, v131, 0x3a800000, v200
	v_rsq_f32_e32 v161, v131
	v_add_u32_e32 v131, 32, v170
	v_lshlrev_b32_e32 v162, 1, v131
	v_and_b32_e32 v162, 0xffffff80, v162
	v_and_or_b32 v131, v131, 63, s0
	v_add_u32_e32 v162, v131, v162
	v_ashrrev_i32_e32 v163, 31, v162
	v_lshlrev_b64 v[162:163], 6, v[162:163]
	v_lshl_add_u64 v[162:163], v[128:129], 0, v[162:163]
	s_waitcnt vmcnt(0)
	v_add_f32_e32 v131, v224, v225
	v_add_f32_e32 v162, v226, v227
	v_add_f32_e32 v131, v131, v162
	ds_bpermute_b32 v162, v160, v131
	s_waitcnt lgkmcnt(0)
	v_add_f32_e32 v131, v131, v162
	ds_bpermute_b32 v162, v158, v131
	s_waitcnt lgkmcnt(0)
	v_add_f32_e32 v131, v131, v162
	v_fmamk_f32 v131, v131, 0x3a800000, v200
	v_rsq_f32_e32 v163, v131
	v_add_u32_e32 v131, 48, v170
	v_lshlrev_b32_e32 v162, 1, v131
	v_and_b32_e32 v162, 0xffffff80, v162
	v_and_or_b32 v131, v131, 63, s0
	v_add_u32_e32 v164, v131, v162
	v_ashrrev_i32_e32 v165, 31, v164
	v_lshlrev_b64 v[164:165], 6, v[164:165]
	v_lshl_add_u64 v[164:165], v[128:129], 0, v[164:165]
	s_waitcnt vmcnt(0)
	v_add_f32_e32 v131, v228, v229
	v_add_f32_e32 v162, v230, v231
	v_add_f32_e32 v131, v131, v162
	ds_bpermute_b32 v162, v160, v131
	s_waitcnt lgkmcnt(0)
	v_add_f32_e32 v131, v131, v162
	ds_bpermute_b32 v162, v158, v131
	s_waitcnt lgkmcnt(0)
	v_add_f32_e32 v131, v131, v162
	v_fmamk_f32 v131, v131, 0x3a800000, v200
	v_rsq_f32_e32 v165, v131
	v_ashrrev_i32_e32 v131, 31, v130
	v_lshlrev_b64 v[130:131], 6, v[130:131]
	v_lshl_add_u64 v[130:131], v[128:129], 0, v[130:131]
	s_waitcnt vmcnt(0)
	v_add_f32_e32 v130, v232, v233
	v_add_f32_e32 v131, v234, v235
	v_add_f32_e32 v130, v130, v131
	ds_bpermute_b32 v131, v160, v130
	s_waitcnt lgkmcnt(0)
	v_add_f32_e32 v130, v130, v131
	ds_bpermute_b32 v131, v158, v130
	s_waitcnt lgkmcnt(0)
	v_add_f32_e32 v130, v130, v131
	v_fmamk_f32 v130, v130, 0x3a800000, v200
	v_rsq_f32_e32 v171, v130
	v_add_u32_e32 v130, 0x50, v170
	v_lshlrev_b32_e32 v131, 1, v130
	v_and_b32_e32 v131, 0xffffff80, v131
	v_and_or_b32 v130, v130, 63, s0
	v_add_u32_e32 v130, v130, v131
	v_ashrrev_i32_e32 v131, 31, v130
	v_lshlrev_b64 v[130:131], 6, v[130:131]
	v_lshl_add_u64 v[130:131], v[128:129], 0, v[130:131]
	s_waitcnt vmcnt(0)
	v_add_f32_e32 v130, v236, v237
	v_add_f32_e32 v131, v238, v239
	v_add_f32_e32 v130, v130, v131
	ds_bpermute_b32 v131, v160, v130
	s_waitcnt lgkmcnt(0)
	v_add_f32_e32 v130, v130, v131
	ds_bpermute_b32 v131, v158, v130
	s_waitcnt lgkmcnt(0)
	v_add_f32_e32 v130, v130, v131
	v_fmamk_f32 v130, v130, 0x3a800000, v200
	v_rsq_f32_e32 v172, v130
	v_add_u32_e32 v130, 0x60, v170
	v_lshlrev_b32_e32 v131, 1, v130
	v_and_b32_e32 v131, 0xffffff80, v131
	v_and_or_b32 v130, v130, 63, s0
	v_add_u32_e32 v130, v130, v131
	v_ashrrev_i32_e32 v131, 31, v130
	v_lshlrev_b64 v[130:131], 6, v[130:131]
	v_lshl_add_u64 v[130:131], v[128:129], 0, v[130:131]
	s_waitcnt vmcnt(0)
	v_add_f32_e32 v130, v240, v241
	v_add_f32_e32 v131, v242, v243
	v_add_f32_e32 v130, v130, v131
	ds_bpermute_b32 v131, v160, v130
	s_waitcnt lgkmcnt(0)
	v_add_f32_e32 v130, v130, v131
	ds_bpermute_b32 v131, v158, v130
	s_waitcnt lgkmcnt(0)
	v_add_f32_e32 v130, v130, v131
	v_fmamk_f32 v130, v130, 0x3a800000, v200
	v_rsq_f32_e32 v166, v130
	v_add_u32_e32 v130, 0x70, v170
	v_lshlrev_b32_e32 v131, 1, v130
	v_and_b32_e32 v131, 0xffffff80, v131
	v_and_or_b32 v130, v130, 63, s0
	v_add_u32_e32 v130, v130, v131
	v_ashrrev_i32_e32 v131, 31, v130
	v_lshlrev_b64 v[130:131], 6, v[130:131]
	v_lshl_add_u64 v[128:129], v[128:129], 0, v[130:131]
	s_waitcnt vmcnt(0)
	v_add_f32_e32 v128, v244, v245
	v_add_f32_e32 v129, v246, v247
	v_add_f32_e32 v128, v128, v129
	ds_bpermute_b32 v129, v160, v128
	v_or_b32_e32 v130, s0, v141
	s_cselect_b64 s[0:1], -1, 0
	s_cmp_lt_i32 s75, 1
	s_waitcnt lgkmcnt(0)
	v_add_f32_e32 v128, v128, v129
	ds_bpermute_b32 v129, v158, v128
	s_waitcnt lgkmcnt(0)
	v_add_f32_e32 v128, v128, v129
	v_fmamk_f32 v128, v128, 0x3a800000, v200
	v_rsq_f32_e32 v128, v128
	v_lshlrev_b32_e32 v129, 2, v152
	v_and_or_b32 v129, v129, 60, v154
	v_lshlrev_b32_e32 v129, 2, v129
	ds_bpermute_b32 v164, v129, v156
	ds_bpermute_b32 v162, v129, v161
	ds_bpermute_b32 v160, v129, v163
	ds_bpermute_b32 v158, v129, v165
	ds_bpermute_b32 v156, v129, v171
	ds_bpermute_b32 v154, v129, v172
	ds_bpermute_b32 v152, v129, v166
	ds_bpermute_b32 v128, v129, v128
	v_xor_b32_e32 v129, 16, v219
	v_xor_b32_e32 v161, 32, v219
	v_cmp_lt_i32_e64 s[44:45], v129, v159
	v_cmp_lt_i32_e64 s[46:47], v161, v159
	s_cbranch_scc1 .LBB0_585
	s_cmp_eq_u32 s75, 1
	s_mov_b64 s[10:11], -1
	s_cbranch_scc0 .LBB0_584
	s_andn2_b64 vcc, exec, s[94:95]
	s_cbranch_vccnz .LBB0_583
	v_ashrrev_i32_e32 v131, 31, v130
	v_lshlrev_b64 v[166:167], 8, v[130:131]
	v_lshl_add_u64 v[194:195], v[142:143], 0, v[166:167]
	global_load_dwordx4 v[170:173], v[194:195], off offset:32
	global_load_dwordx4 v[174:177], v[194:195], off offset:48
	global_load_dwordx4 v[166:169], v[194:195], off
	s_nop 0
	global_load_dwordx4 v[194:197], v[194:195], off offset:16
	s_waitcnt lgkmcnt(7)
	v_pk_mul_f32 v[202:203], v[118:119], v[164:165] op_sel_hi:[1,0]
	v_pk_mul_f32 v[178:179], v[126:127], v[164:165] op_sel_hi:[1,0]
	v_pk_mul_f32 v[206:207], v[116:117], v[164:165] op_sel_hi:[1,0]
	v_pk_mul_f32 v[198:199], v[124:125], v[164:165] op_sel_hi:[1,0]
	s_waitcnt vmcnt(1)
	v_mov_b32_e32 v212, v167
	s_waitcnt vmcnt(0)
	v_mov_b32_e32 v208, v195
	v_mov_b32_e32 v209, v197
	v_pk_mul_f32 v[210:211], v[202:203], v[208:209]
	v_mov_b32_e32 v213, v169
	v_mov_b32_e32 v195, v196
	v_mov_b32_e32 v167, v168
	v_pk_mul_f32 v[214:215], v[206:207], v[212:213]
	v_pk_fma_f32 v[196:197], v[178:179], v[194:195], v[210:211] neg_lo:[0,0,1] neg_hi:[0,0,1]
	v_pk_mul_f32 v[168:169], v[202:203], v[194:195]
	v_pk_mul_f32 v[194:195], v[206:207], v[166:167]
	v_pk_fma_f32 v[210:211], v[198:199], v[166:167], v[214:215] neg_lo:[0,0,1] neg_hi:[0,0,1]
	v_pk_fma_f32 v[166:167], v[178:179], v[208:209], v[168:169]
	v_pk_fma_f32 v[168:169], v[198:199], v[212:213], v[194:195]
	v_pk_mul_f32 v[198:199], v[114:115], v[164:165] op_sel_hi:[1,0]
	v_pk_mul_f32 v[202:203], v[112:113], v[164:165] op_sel_hi:[1,0]
	v_mov_b32_e32 v206, v175
	v_mov_b32_e32 v207, v177
	v_mov_b32_e32 v212, v171
	v_mov_b32_e32 v213, v173
	v_pk_mul_f32 v[178:179], v[122:123], v[164:165] op_sel_hi:[1,0]
	v_pk_mul_f32 v[194:195], v[120:121], v[164:165] op_sel_hi:[1,0]
	v_pk_mul_f32 v[208:209], v[198:199], v[206:207]
	v_pk_mul_f32 v[214:215], v[202:203], v[212:213]
	v_mov_b32_e32 v175, v176
	v_mov_b32_e32 v171, v172
	v_pk_fma_f32 v[176:177], v[178:179], v[174:175], v[208:209] neg_lo:[0,0,1] neg_hi:[0,0,1]
	v_pk_fma_f32 v[172:173], v[194:195], v[170:171], v[214:215] neg_lo:[0,0,1] neg_hi:[0,0,1]
	v_pk_mul_f32 v[174:175], v[198:199], v[174:175]
	v_pk_mul_f32 v[170:171], v[202:203], v[170:171]
	v_cvt_pk_bf16_f32 v172, v172, v173
	v_cvt_pk_bf16_f32 v173, v176, v177
	v_lshlrev_b64 v[176:177], 7, v[130:131]
	v_pk_fma_f32 v[174:175], v[178:179], v[206:207], v[174:175]
	v_pk_fma_f32 v[178:179], v[194:195], v[212:213], v[170:171]
	v_cvt_pk_bf16_f32 v170, v210, v211
	v_cvt_pk_bf16_f32 v171, v196, v197
	v_lshl_add_u64 v[176:177], v[144:145], 0, v[176:177]
	global_store_dwordx4 v[176:177], v[170:173], off
	v_cvt_pk_bf16_f32 v168, v168, v169
	v_cvt_pk_bf16_f32 v169, v166, v167
	v_cvt_pk_bf16_f32 v170, v178, v179
	v_cvt_pk_bf16_f32 v171, v174, v175
	global_store_dwordx4 v[176:177], v[168:171], off offset:64

.LBB0_801:
	v_lshl_add_u32 v156, s58, 8, v141
	v_ashrrev_i32_e32 v157, 31, v156
	v_lshl_add_u64 v[146:147], v[156:157], 4, s[14:15]
	global_load_dwordx4 v[176:179], v[146:147], off offset:256
	global_load_dwordx4 v[194:197], v[146:147], off offset:512
	global_load_dwordx4 v[206:209], v[146:147], off offset:768
	global_load_dwordx4 v[210:213], v[146:147], off offset:2048
	global_load_dwordx4 v[214:217], v[146:147], off offset:2304
	global_load_dwordx4 v[220:223], v[146:147], off offset:2560
	global_load_dwordx4 v[224:227], v[146:147], off offset:2816
	global_load_dwordx4 v[146:149], v[146:147], off
	v_or_b32_e32 v154, 16, v156
	v_ashrrev_i32_e32 v155, 31, v154
	v_or_b32_e32 v158, 32, v156
	v_ashrrev_i32_e32 v159, 31, v158
	s_waitcnt vmcnt(0)
	v_or_b32_e32 v160, 48, v156
	v_ashrrev_i32_e32 v161, 31, v160
	v_add_u32_e32 v162, 0x80, v156
	v_ashrrev_i32_e32 v163, 31, v162
	v_add_u32_e32 v164, 0x90, v156
	v_ashrrev_i32_e32 v165, 31, v164
	s_lshl_b32 s10, s57, 8
	s_ashr_i32 s11, s10, 31
	s_lshl_b64 s[16:17], s[10:11], 1
	s_mov_b64 s[10:11], -1
	s_and_b64 vcc, exec, s[40:41]
	s_waitcnt vmcnt(0)
	v_mov_b32_e32 v150, v147
	v_mov_b32_e32 v151, v148
	v_mov_b32_e32 v147, v149
	v_pk_add_f32 v[146:147], v[150:151], v[146:147]
	s_nop 0
	v_add_f32_e32 v140, v146, v147
	v_lshl_add_u64 v[146:147], v[154:155], 4, s[14:15]
	v_add_f32_e32 v140, 0, v140
	v_fmamk_f32 v140, v140, 0x3b800000, v200
	v_rsq_f32_e32 v140, v140
	s_waitcnt vmcnt(0)
	v_mov_b32_e32 v146, v176
	v_mov_b32_e32 v147, v177
	v_mov_b32_e32 v148, v178
	v_mov_b32_e32 v149, v179
	v_mov_b32_e32 v150, v147
	v_mov_b32_e32 v151, v148
	v_mov_b32_e32 v147, v149
	v_pk_add_f32 v[146:147], v[150:151], v[146:147]
	v_pk_mul_f32 v[124:125], v[124:125], v[140:141] op_sel_hi:[1,0]
	v_add_f32_e32 v142, v146, v147
	v_lshl_add_u64 v[146:147], v[158:159], 4, s[14:15]
	v_add_f32_e32 v142, 0, v142
	v_fmamk_f32 v142, v142, 0x3b800000, v200
	v_rsq_f32_e32 v142, v142
	v_pk_mul_f32 v[126:127], v[126:127], v[140:141] op_sel_hi:[1,0]
	v_pk_mul_f32 v[118:119], v[118:119], v[140:141] op_sel_hi:[1,0]
	v_pk_mul_f32 v[116:117], v[116:117], v[140:141] op_sel_hi:[1,0]
	v_pk_mul_f32 v[108:109], v[108:109], v[142:143] op_sel_hi:[1,0]
	v_pk_mul_f32 v[110:111], v[110:111], v[142:143] op_sel_hi:[1,0]
	v_pk_mul_f32 v[102:103], v[102:103], v[142:143] op_sel_hi:[1,0]
	v_pk_mul_f32 v[100:101], v[100:101], v[142:143] op_sel_hi:[1,0]
	s_waitcnt vmcnt(0)
	v_mov_b32_e32 v146, v194
	v_mov_b32_e32 v147, v195
	v_mov_b32_e32 v148, v196
	v_mov_b32_e32 v149, v197
	v_mov_b32_e32 v150, v147
	v_mov_b32_e32 v151, v148
	v_mov_b32_e32 v147, v149
	v_pk_add_f32 v[146:147], v[150:151], v[146:147]
	s_nop 0
	v_add_f32_e32 v144, v146, v147
	v_lshl_add_u64 v[146:147], v[160:161], 4, s[14:15]
	v_add_f32_e32 v144, 0, v144
	v_fmamk_f32 v144, v144, 0x3b800000, v200
	v_rsq_f32_e32 v144, v144
	s_waitcnt vmcnt(0)
	v_mov_b32_e32 v146, v206
	v_mov_b32_e32 v147, v207
	v_mov_b32_e32 v148, v208
	v_mov_b32_e32 v149, v209
	v_mov_b32_e32 v150, v147
	v_mov_b32_e32 v151, v148
	v_mov_b32_e32 v147, v149
	v_lshl_add_u64 v[148:149], v[162:163], 4, s[14:15]
	v_pk_add_f32 v[146:147], v[150:151], v[146:147]
	v_add_f32_e32 v146, v146, v147
	v_pk_mul_f32 v[92:93], v[92:93], v[144:145] op_sel_hi:[1,0]
	v_add_f32_e32 v146, 0, v146
	v_fmamk_f32 v146, v146, 0x3b800000, v200
	v_rsq_f32_e32 v146, v146
	v_pk_mul_f32 v[94:95], v[94:95], v[144:145] op_sel_hi:[1,0]
	v_pk_mul_f32 v[86:87], v[86:87], v[144:145] op_sel_hi:[1,0]
	v_pk_mul_f32 v[84:85], v[84:85], v[144:145] op_sel_hi:[1,0]
	s_waitcnt vmcnt(0)
	v_mov_b32_e32 v148, v210
	v_mov_b32_e32 v149, v211
	v_mov_b32_e32 v150, v212
	v_mov_b32_e32 v151, v213
	v_mov_b32_e32 v152, v149
	v_mov_b32_e32 v153, v150
	v_mov_b32_e32 v149, v151
	v_lshl_add_u64 v[150:151], v[164:165], 4, s[14:15]
	v_pk_add_f32 v[148:149], v[152:153], v[148:149]
	v_add_f32_e32 v147, v148, v149
	v_add_f32_e32 v147, 0, v147
	v_fmamk_f32 v147, v147, 0x3b800000, v200
	v_rsq_f32_e32 v148, v147
	s_waitcnt vmcnt(0)
	v_mov_b32_e32 v150, v214
	v_mov_b32_e32 v151, v215
	v_mov_b32_e32 v152, v216
	v_mov_b32_e32 v153, v217
	v_mov_b32_e32 v166, v151
	v_mov_b32_e32 v167, v152
	v_mov_b32_e32 v151, v153
	v_pk_add_f32 v[150:151], v[166:167], v[150:151]
	v_add_u32_e32 v166, 0xa0, v156
	v_ashrrev_i32_e32 v167, 31, v166
	v_lshl_add_u64 v[152:153], v[166:167], 4, s[14:15]
	v_add_f32_e32 v147, v150, v151
	v_add_f32_e32 v147, 0, v147
	v_fmamk_f32 v147, v147, 0x3b800000, v200
	v_rsq_f32_e32 v150, v147
	v_pk_mul_f32 v[60:61], v[60:61], v[148:149] op_sel_hi:[1,0]
	v_pk_mul_f32 v[62:63], v[62:63], v[148:149] op_sel_hi:[1,0]
	v_pk_mul_f32 v[54:55], v[54:55], v[148:149] op_sel_hi:[1,0]
	v_pk_mul_f32 v[52:53], v[52:53], v[148:149] op_sel_hi:[1,0]
	v_pk_mul_f32 v[44:45], v[44:45], v[150:151] op_sel_hi:[1,0]
	v_pk_mul_f32 v[46:47], v[46:47], v[150:151] op_sel_hi:[1,0]
	v_pk_mul_f32 v[38:39], v[38:39], v[150:151] op_sel_hi:[1,0]
	v_pk_mul_f32 v[36:37], v[36:37], v[150:151] op_sel_hi:[1,0]
	s_waitcnt vmcnt(0)
	v_mov_b32_e32 v168, v220
	v_mov_b32_e32 v169, v221
	v_mov_b32_e32 v170, v222
	v_mov_b32_e32 v171, v223
	v_mov_b32_e32 v152, v169
	v_mov_b32_e32 v153, v170
	v_mov_b32_e32 v169, v171
	v_pk_add_f32 v[152:153], v[152:153], v[168:169]
	v_add_u32_e32 v168, 0xb0, v156
	v_ashrrev_i32_e32 v169, 31, v168
	v_lshl_add_u64 v[170:171], v[168:169], 4, s[14:15]
	v_lshlrev_b64 v[156:157], 11, v[156:157]
	v_add_f32_e32 v147, v152, v153
	v_add_f32_e32 v147, 0, v147
	v_fmamk_f32 v147, v147, 0x3b800000, v200
	v_rsq_f32_e32 v152, v147
	s_waitcnt vmcnt(0)
	v_mov_b32_e32 v170, v224
	v_mov_b32_e32 v171, v225
	v_mov_b32_e32 v172, v226
	v_mov_b32_e32 v173, v227
	v_mov_b32_e32 v174, v171
	v_mov_b32_e32 v175, v172
	v_mov_b32_e32 v171, v173
	v_pk_mul_f32 v[172:173], v[122:123], v[140:141] op_sel_hi:[1,0]
	v_pk_mul_f32 v[122:123], v[120:121], v[140:141] op_sel_hi:[1,0]
	v_cvt_pk_bf16_f32 v120, v124, v125
	v_lshl_add_u64 v[124:125], s[18:19], 0, v[156:157]
	v_lshl_add_u64 v[124:125], v[124:125], 0, s[16:17]
	v_lshl_add_u64 v[124:125], v[124:125], 0, s[64:65]
	v_cvt_pk_bf16_f32 v121, v126, v127
	v_cvt_pk_bf16_f32 v122, v122, v123
	v_cvt_pk_bf16_f32 v123, v172, v173
	v_lshl_add_u64 v[124:125], v[124:125], 0, v[180:181]
	global_store_dwordx4 v[124:125], v[120:123], off
	v_pk_add_f32 v[170:171], v[174:175], v[170:171]
	v_pk_mul_f32 v[28:29], v[28:29], v[152:153] op_sel_hi:[1,0]
	v_pk_mul_f32 v[120:121], v[114:115], v[140:141] op_sel_hi:[1,0]
	v_pk_mul_f32 v[114:115], v[112:113], v[140:141] op_sel_hi:[1,0]
	v_cvt_pk_bf16_f32 v112, v116, v117
	v_cvt_pk_bf16_f32 v113, v118, v119
	v_cvt_pk_bf16_f32 v114, v114, v115
	v_cvt_pk_bf16_f32 v115, v120, v121
	global_store_dwordx4 v[124:125], v[112:115], off offset:256
	v_add_f32_e32 v147, v170, v171
	v_add_f32_e32 v147, 0, v147
	v_lshlrev_b64 v[112:113], 11, v[154:155]
	v_pk_mul_f32 v[114:115], v[106:107], v[142:143] op_sel_hi:[1,0]
	v_pk_mul_f32 v[106:107], v[104:105], v[142:143] op_sel_hi:[1,0]
	v_cvt_pk_bf16_f32 v104, v108, v109
	v_lshl_add_u64 v[108:109], s[18:19], 0, v[112:113]
	v_lshl_add_u64 v[108:109], v[108:109], 0, s[16:17]
	v_lshl_add_u64 v[108:109], v[108:109], 0, s[64:65]
	v_cvt_pk_bf16_f32 v105, v110, v111
	v_cvt_pk_bf16_f32 v106, v106, v107
	v_cvt_pk_bf16_f32 v107, v114, v115
	v_lshl_add_u64 v[108:109], v[108:109], 0, v[180:181]
	global_store_dwordx4 v[108:109], v[104:107], off
	v_fmamk_f32 v147, v147, 0x3b800000, v200
	v_pk_mul_f32 v[76:77], v[76:77], v[146:147] op_sel_hi:[1,0]
	v_pk_mul_f32 v[104:105], v[98:99], v[142:143] op_sel_hi:[1,0]
	v_pk_mul_f32 v[98:99], v[96:97], v[142:143] op_sel_hi:[1,0]
	v_cvt_pk_bf16_f32 v96, v100, v101
	v_cvt_pk_bf16_f32 v97, v102, v103
	v_cvt_pk_bf16_f32 v98, v98, v99
	v_cvt_pk_bf16_f32 v99, v104, v105
	global_store_dwordx4 v[108:109], v[96:99], off offset:256
	v_pk_mul_f32 v[78:79], v[78:79], v[146:147] op_sel_hi:[1,0]
	v_pk_mul_f32 v[70:71], v[70:71], v[146:147] op_sel_hi:[1,0]
	v_lshlrev_b64 v[96:97], 11, v[158:159]
	v_pk_mul_f32 v[98:99], v[90:91], v[144:145] op_sel_hi:[1,0]
	v_pk_mul_f32 v[90:91], v[88:89], v[144:145] op_sel_hi:[1,0]
	v_cvt_pk_bf16_f32 v88, v92, v93
	v_lshl_add_u64 v[92:93], s[18:19], 0, v[96:97]
	v_lshl_add_u64 v[92:93], v[92:93], 0, s[16:17]
	v_lshl_add_u64 v[92:93], v[92:93], 0, s[64:65]
	v_cvt_pk_bf16_f32 v89, v94, v95
	v_cvt_pk_bf16_f32 v90, v90, v91
	v_cvt_pk_bf16_f32 v91, v98, v99
	v_lshl_add_u64 v[92:93], v[92:93], 0, v[180:181]
	global_store_dwordx4 v[92:93], v[88:91], off
	v_pk_mul_f32 v[68:69], v[68:69], v[146:147] op_sel_hi:[1,0]
	v_rsq_f32_e32 v170, v147
	v_pk_mul_f32 v[88:89], v[82:83], v[144:145] op_sel_hi:[1,0]
	v_pk_mul_f32 v[82:83], v[80:81], v[144:145] op_sel_hi:[1,0]
	v_cvt_pk_bf16_f32 v80, v84, v85
	v_cvt_pk_bf16_f32 v81, v86, v87
	v_cvt_pk_bf16_f32 v82, v82, v83
	v_cvt_pk_bf16_f32 v83, v88, v89
	global_store_dwordx4 v[92:93], v[80:83], off offset:256
	v_pk_mul_f32 v[30:31], v[30:31], v[152:153] op_sel_hi:[1,0]
	v_pk_mul_f32 v[22:23], v[22:23], v[152:153] op_sel_hi:[1,0]
	v_lshlrev_b64 v[80:81], 11, v[160:161]
	v_pk_mul_f32 v[82:83], v[74:75], v[146:147] op_sel_hi:[1,0]
	v_pk_mul_f32 v[74:75], v[72:73], v[146:147] op_sel_hi:[1,0]
	v_cvt_pk_bf16_f32 v72, v76, v77
	v_lshl_add_u64 v[76:77], s[18:19], 0, v[80:81]
	v_lshl_add_u64 v[76:77], v[76:77], 0, s[16:17]
	v_lshl_add_u64 v[76:77], v[76:77], 0, s[64:65]
	v_cvt_pk_bf16_f32 v73, v78, v79
	v_cvt_pk_bf16_f32 v74, v74, v75
	v_cvt_pk_bf16_f32 v75, v82, v83
	v_lshl_add_u64 v[76:77], v[76:77], 0, v[180:181]
	global_store_dwordx4 v[76:77], v[72:75], off
	v_pk_mul_f32 v[20:21], v[20:21], v[152:153] op_sel_hi:[1,0]
	v_pk_mul_f32 v[12:13], v[12:13], v[170:171] op_sel_hi:[1,0]
	v_pk_mul_f32 v[72:73], v[66:67], v[146:147] op_sel_hi:[1,0]
	v_pk_mul_f32 v[66:67], v[64:65], v[146:147] op_sel_hi:[1,0]
	v_cvt_pk_bf16_f32 v64, v68, v69
	v_cvt_pk_bf16_f32 v65, v70, v71
	v_cvt_pk_bf16_f32 v66, v66, v67
	v_cvt_pk_bf16_f32 v67, v72, v73
	global_store_dwordx4 v[76:77], v[64:67], off offset:256
	v_pk_mul_f32 v[14:15], v[14:15], v[170:171] op_sel_hi:[1,0]
	v_pk_mul_f32 v[6:7], v[6:7], v[170:171] op_sel_hi:[1,0]
	v_lshlrev_b64 v[64:65], 11, v[162:163]
	v_pk_mul_f32 v[66:67], v[58:59], v[148:149] op_sel_hi:[1,0]
	v_pk_mul_f32 v[58:59], v[56:57], v[148:149] op_sel_hi:[1,0]
	v_cvt_pk_bf16_f32 v56, v60, v61
	v_lshl_add_u64 v[60:61], s[18:19], 0, v[64:65]
	v_lshl_add_u64 v[60:61], v[60:61], 0, s[16:17]
	v_lshl_add_u64 v[60:61], v[60:61], 0, s[64:65]
	v_cvt_pk_bf16_f32 v57, v62, v63
	v_cvt_pk_bf16_f32 v58, v58, v59
	v_cvt_pk_bf16_f32 v59, v66, v67
	v_lshl_add_u64 v[60:61], v[60:61], 0, v[180:181]
	global_store_dwordx4 v[60:61], v[56:59], off
	v_pk_mul_f32 v[4:5], v[4:5], v[170:171] op_sel_hi:[1,0]
	s_nop 0
	v_pk_mul_f32 v[56:57], v[50:51], v[148:149] op_sel_hi:[1,0]
	v_pk_mul_f32 v[50:51], v[48:49], v[148:149] op_sel_hi:[1,0]
	v_cvt_pk_bf16_f32 v48, v52, v53
	v_cvt_pk_bf16_f32 v49, v54, v55
	v_cvt_pk_bf16_f32 v50, v50, v51
	v_cvt_pk_bf16_f32 v51, v56, v57
	global_store_dwordx4 v[60:61], v[48:51], off offset:256
	s_nop 1
	v_lshlrev_b64 v[48:49], 11, v[164:165]
	v_pk_mul_f32 v[50:51], v[42:43], v[150:151] op_sel_hi:[1,0]
	v_pk_mul_f32 v[42:43], v[40:41], v[150:151] op_sel_hi:[1,0]
	v_cvt_pk_bf16_f32 v40, v44, v45
	v_lshl_add_u64 v[44:45], s[18:19], 0, v[48:49]
	v_lshl_add_u64 v[44:45], v[44:45], 0, s[16:17]
	v_lshl_add_u64 v[44:45], v[44:45], 0, s[64:65]
	v_cvt_pk_bf16_f32 v41, v46, v47
	v_cvt_pk_bf16_f32 v42, v42, v43
	v_cvt_pk_bf16_f32 v43, v50, v51
	v_lshl_add_u64 v[44:45], v[44:45], 0, v[180:181]
	global_store_dwordx4 v[44:45], v[40:43], off
	s_nop 1
	v_pk_mul_f32 v[40:41], v[34:35], v[150:151] op_sel_hi:[1,0]
	v_pk_mul_f32 v[34:35], v[32:33], v[150:151] op_sel_hi:[1,0]
	v_cvt_pk_bf16_f32 v32, v36, v37
	v_cvt_pk_bf16_f32 v33, v38, v39
	v_cvt_pk_bf16_f32 v34, v34, v35
	v_cvt_pk_bf16_f32 v35, v40, v41
	global_store_dwordx4 v[44:45], v[32:35], off offset:256
	s_nop 1
	v_lshlrev_b64 v[32:33], 11, v[166:167]
	v_pk_mul_f32 v[34:35], v[26:27], v[152:153] op_sel_hi:[1,0]
	v_pk_mul_f32 v[26:27], v[24:25], v[152:153] op_sel_hi:[1,0]
	v_cvt_pk_bf16_f32 v24, v28, v29
	v_lshl_add_u64 v[28:29], s[18:19], 0, v[32:33]
	v_lshl_add_u64 v[28:29], v[28:29], 0, s[16:17]
	v_lshl_add_u64 v[28:29], v[28:29], 0, s[64:65]
	v_cvt_pk_bf16_f32 v25, v30, v31
	v_cvt_pk_bf16_f32 v26, v26, v27
	v_cvt_pk_bf16_f32 v27, v34, v35
	v_lshl_add_u64 v[28:29], v[28:29], 0, v[180:181]
	global_store_dwordx4 v[28:29], v[24:27], off
	s_nop 1
	v_pk_mul_f32 v[24:25], v[18:19], v[152:153] op_sel_hi:[1,0]
	v_pk_mul_f32 v[18:19], v[16:17], v[152:153] op_sel_hi:[1,0]
	v_cvt_pk_bf16_f32 v16, v20, v21
	v_cvt_pk_bf16_f32 v17, v22, v23
	v_cvt_pk_bf16_f32 v18, v18, v19
	v_cvt_pk_bf16_f32 v19, v24, v25
	global_store_dwordx4 v[28:29], v[16:19], off offset:256
	s_nop 1
	v_lshlrev_b64 v[16:17], 11, v[168:169]
	v_pk_mul_f32 v[18:19], v[10:11], v[170:171] op_sel_hi:[1,0]
	v_pk_mul_f32 v[10:11], v[8:9], v[170:171] op_sel_hi:[1,0]
	v_cvt_pk_bf16_f32 v8, v12, v13
	v_lshl_add_u64 v[12:13], s[18:19], 0, v[16:17]
	v_lshl_add_u64 v[12:13], v[12:13], 0, s[16:17]
	v_lshl_add_u64 v[12:13], v[12:13], 0, s[64:65]
	v_cvt_pk_bf16_f32 v9, v14, v15
	v_cvt_pk_bf16_f32 v10, v10, v11
	v_cvt_pk_bf16_f32 v11, v18, v19
	v_lshl_add_u64 v[12:13], v[12:13], 0, v[180:181]
	global_store_dwordx4 v[12:13], v[8:11], off
	s_nop 1
	v_pk_mul_f32 v[8:9], v[2:3], v[170:171] op_sel_hi:[1,0]
	v_pk_mul_f32 v[2:3], v[0:1], v[170:171] op_sel_hi:[1,0]
	v_cvt_pk_bf16_f32 v0, v4, v5
	v_cvt_pk_bf16_f32 v1, v6, v7
	v_cvt_pk_bf16_f32 v2, v2, v3
	v_cvt_pk_bf16_f32 v3, v8, v9
	global_store_dwordx4 v[12:13], v[0:3], off offset:256
	s_cbranch_vccnz .LBB0_785
	s_andn2_b64 vcc, exec, s[8:9]
	s_cbranch_vccnz .LBB0_784
	s_mov_b32 s100, 1
	s_branch .LBB0_784

.LBB0_847:
	v_mov_b32_e32 v145, v165
	v_and_b32_e32 v157, 64, v219
	v_lshrrev_b32_e32 v146, 31, v145
	v_add_u32_e32 v148, v145, v146
	v_and_b32_e32 v146, 0x3ffffffe, v148
	v_sub_u32_e32 v146, v145, v146
	v_lshlrev_b32_e32 v146, 2, v146
	v_ashrrev_i32_e32 v147, 31, v146
	v_lshl_add_u64 v[150:151], v[146:147], 2, s[18:19]
	v_xor_b32_e32 v146, 1, v219
	v_add_u32_e32 v147, 64, v157
	s_lshl_b32 s0, s34, 8
	v_cmp_lt_i32_e32 vcc, v146, v147
	s_add_i32 s0, s0, s52
	v_ashrrev_i32_e32 v156, 1, v148
	v_cndmask_b32_e32 v146, v219, v146, vcc
	v_lshlrev_b32_e32 v158, 2, v146
	v_and_b32_e32 v146, 0xffffff80, v148
	v_and_or_b32 v147, v156, 63, s0
	v_add_u32_e32 v152, v147, v146
	v_ashrrev_i32_e32 v153, 31, v152
	v_lshlrev_b64 v[146:147], 5, v[152:153]
	v_lshl_add_u64 v[146:147], v[150:151], 0, v[146:147]
	v_add_co_u32_e32 v178, vcc, 0x1000, v146
	v_addc_co_u32_e32 v179, vcc, 0, v147, vcc
	global_load_dwordx4 v[160:163], v[146:147], off offset:1024
	global_load_dwordx4 v[174:177], v[178:179], off
	global_load_dwordx4 v[194:197], v[178:179], off offset:1024
	global_load_dwordx4 v[146:149], v[146:147], off
	v_and_b32_e32 v145, 15, v145
	v_lshlrev_b32_e32 v145, 3, v145
	v_lshl_or_b32 v145, v157, 2, v145
	s_cmp_gt_i32 s62, 3
	v_or_b32_e32 v144, s0, v137
	s_cselect_b64 s[34:35], -1, 0
	s_mov_b64 s[16:17], -1
	v_lshlrev_b32_e32 v180, 1, v136
	s_waitcnt vmcnt(0)
	v_mov_b32_e32 v154, v147
	v_mov_b32_e32 v155, v148
	v_mov_b32_e32 v147, v149
	v_pk_add_f32 v[146:147], v[154:155], v[146:147]
	s_nop 0
	v_add_f32_e32 v146, v146, v147
	ds_bpermute_b32 v147, v158, v146
	s_waitcnt lgkmcnt(0)
	v_add_f32_e32 v146, v146, v147
	v_fmamk_f32 v146, v146, 0x3b2aaaab, v200
	v_rsq_f32_e32 v153, v146
	v_add_u32_e32 v146, 32, v156
	v_lshlrev_b32_e32 v147, 1, v146
	v_and_b32_e32 v147, 0xffffff80, v147
	v_and_or_b32 v146, v146, 63, s0
	v_add_u32_e32 v146, v146, v147
	v_ashrrev_i32_e32 v147, 31, v146
	v_lshlrev_b64 v[146:147], 5, v[146:147]
	v_lshl_add_u64 v[146:147], v[150:151], 0, v[146:147]
	ds_bpermute_b32 v173, v145, v153 offset:128
	s_waitcnt vmcnt(0)
	v_mov_b32_e32 v146, v160
	v_mov_b32_e32 v147, v161
	v_mov_b32_e32 v148, v162
	v_mov_b32_e32 v149, v163
	v_add_f32_e32 v146, v146, v147
	v_add_f32_e32 v147, v148, v149
	v_add_f32_e32 v146, v146, v147
	ds_bpermute_b32 v147, v158, v146
	s_waitcnt lgkmcnt(0)
	v_add_f32_e32 v146, v146, v147
	v_fmamk_f32 v146, v146, 0x3b2aaaab, v200
	v_rsq_f32_e32 v154, v146
	v_add_u32_e32 v146, 0x80, v152
	v_ashrrev_i32_e32 v147, 31, v146
	v_lshlrev_b64 v[146:147], 5, v[146:147]
	v_lshl_add_u64 v[146:147], v[150:151], 0, v[146:147]
	ds_bpermute_b32 v172, v145, v154
	ds_bpermute_b32 v171, v145, v154 offset:128
	s_waitcnt vmcnt(0)
	v_mov_b32_e32 v146, v174
	v_mov_b32_e32 v147, v175
	v_mov_b32_e32 v148, v176
	v_mov_b32_e32 v149, v177
	v_add_f32_e32 v146, v146, v147
	v_add_f32_e32 v147, v148, v149
	v_add_f32_e32 v146, v146, v147
	ds_bpermute_b32 v147, v158, v146
	s_waitcnt lgkmcnt(0)
	v_add_f32_e32 v146, v146, v147
	v_fmamk_f32 v146, v146, 0x3b2aaaab, v200
	v_rsq_f32_e32 v152, v146
	v_add_u32_e32 v146, 0x60, v156
	v_lshlrev_b32_e32 v147, 1, v146
	v_and_b32_e32 v147, 0xffffff80, v147
	v_and_or_b32 v146, v146, 63, s0
	v_add_u32_e32 v146, v146, v147
	v_ashrrev_i32_e32 v147, 31, v146
	v_lshlrev_b64 v[146:147], 5, v[146:147]
	v_lshl_add_u64 v[146:147], v[150:151], 0, v[146:147]
	ds_bpermute_b32 v170, v145, v152
	ds_bpermute_b32 v169, v145, v152 offset:128
	s_lshl_b32 s0, s62, 2
	s_add_i32 s0, s58, s0
	s_mulk_i32 s0, 0xc0
	s_ashr_i32 s1, s0, 31
	s_cmp_lt_i32 s62, 4
	s_waitcnt vmcnt(0)
	v_mov_b32_e32 v146, v194
	v_mov_b32_e32 v147, v195
	v_mov_b32_e32 v148, v196
	v_mov_b32_e32 v149, v197
	v_add_f32_e32 v146, v146, v147
	v_add_f32_e32 v147, v148, v149
	v_add_f32_e32 v146, v146, v147
	ds_bpermute_b32 v147, v158, v146
	s_waitcnt lgkmcnt(0)
	v_add_f32_e32 v146, v146, v147
	v_fmamk_f32 v146, v146, 0x3b2aaaab, v200
	v_rsq_f32_e32 v146, v146
	ds_bpermute_b32 v147, v145, v153
	ds_bpermute_b32 v168, v145, v146
	ds_bpermute_b32 v167, v145, v146 offset:128
	s_waitcnt lgkmcnt(2)
	v_mul_f32_e32 v146, 0x3dd53b94, v147
	v_mov_b32_e32 v147, v146
	v_pk_mul_f32 v[126:127], v[126:127], v[146:147] op_sel_hi:[1,0]
	v_pk_mul_f32 v[124:125], v[124:125], v[146:147] op_sel_hi:[1,0]
	v_ashrrev_i32_e32 v145, 31, v144
	v_pk_mul_f32 v[116:117], v[116:117], v[146:147]
	v_pk_mul_f32 v[120:121], v[120:121], v[146:147]
	v_pk_mul_f32 v[112:113], v[112:113], v[146:147]
	s_cbranch_scc1 .LBB0_849
	v_lshlrev_b64 v[148:149], 8, v[144:145]
	v_lshl_add_u64 v[152:153], v[138:139], 0, v[148:149]
	global_load_dwordx4 v[156:159], v[152:153], off offset:32
	global_load_dwordx4 v[174:177], v[152:153], off offset:48
	global_load_dwordx4 v[148:151], v[152:153], off
	global_load_dwordx4 v[160:163], v[152:153], off offset:16
	v_mov_b32_e32 v147, v146
	v_pk_mul_f32 v[178:179], v[118:119], v[146:147]
	s_mov_b64 s[16:17], 0
	s_waitcnt vmcnt(3)
	v_mov_b32_e32 v198, v157
	v_mov_b32_e32 v199, v159
	s_waitcnt vmcnt(1)
	v_mov_b32_e32 v196, v149
	s_waitcnt vmcnt(0)
	v_mov_b32_e32 v194, v161
	v_mov_b32_e32 v195, v163
	v_pk_mul_f32 v[152:153], v[178:179], v[194:195]
	v_mov_b32_e32 v197, v151
	v_mov_b32_e32 v161, v162
	v_mov_b32_e32 v149, v150
	v_pk_mul_f32 v[154:155], v[116:117], v[196:197]
	v_pk_fma_f32 v[152:153], v[126:127], v[160:161], v[152:153] neg_lo:[0,0,1] neg_hi:[0,0,1]
	v_pk_mul_f32 v[150:151], v[178:179], v[160:161]
	v_pk_mul_f32 v[160:161], v[116:117], v[148:149]
	v_pk_fma_f32 v[154:155], v[124:125], v[148:149], v[154:155] neg_lo:[0,0,1] neg_hi:[0,0,1]
	v_pk_fma_f32 v[148:149], v[126:127], v[194:195], v[150:151]
	v_pk_fma_f32 v[150:151], v[124:125], v[196:197], v[160:161]
	v_pk_mul_f32 v[194:195], v[114:115], v[146:147]
	v_mov_b32_e32 v196, v175
	v_mov_b32_e32 v197, v177
	v_pk_mul_f32 v[178:179], v[122:123], v[146:147]
	v_pk_mul_f32 v[160:161], v[194:195], v[196:197]
	v_mov_b32_e32 v175, v176
	v_mov_b32_e32 v157, v158
	v_pk_mul_f32 v[162:163], v[112:113], v[198:199]
	v_pk_fma_f32 v[160:161], v[178:179], v[174:175], v[160:161] neg_lo:[0,0,1] neg_hi:[0,0,1]
	v_pk_mul_f32 v[158:159], v[194:195], v[174:175]
	v_pk_mul_f32 v[174:175], v[112:113], v[156:157]
	v_pk_fma_f32 v[162:163], v[120:121], v[156:157], v[162:163] neg_lo:[0,0,1] neg_hi:[0,0,1]
	v_pk_fma_f32 v[156:157], v[178:179], v[196:197], v[158:159]
	v_pk_fma_f32 v[158:159], v[120:121], v[198:199], v[174:175]
	v_mov_b64_e32 v[174:175], s[20:21]
	v_mad_i64_i32 v[174:175], s[10:11], v144, s50, v[174:175]
	v_lshl_add_u64 v[174:175], s[0:1], 1, v[174:175]
	v_lshl_add_u64 v[178:179], v[174:175], 0, v[180:181]
	v_cvt_pk_bf16_f32 v174, v154, v155
	v_cvt_pk_bf16_f32 v175, v152, v153
	v_cvt_pk_bf16_f32 v176, v162, v163
	v_cvt_pk_bf16_f32 v177, v160, v161
	v_cvt_pk_bf16_f32 v150, v150, v151
	v_cvt_pk_bf16_f32 v151, v148, v149
	v_cvt_pk_bf16_f32 v152, v158, v159
	v_cvt_pk_bf16_f32 v153, v156, v157
	global_store_dwordx4 v[178:179], v[174:177], off offset:256
	global_store_dwordx4 v[178:179], v[150:153], off offset:320
